# two WGs per team (lc<2) start P5 ~6us late (intra-team lag like the P1 scan WGs)
# speedup vs baseline: 1.0065x; 1.0065x over previous
.LBB0_936:
	s_or_b64 exec, exec, s[0:1]
	s_cmp_ge_u32 s80, 2
	s_cbranch_scc1 .Llag_LBB0936
	s_sleep 37
	s_sleep 37
	s_sleep 37
	s_sleep 37
	s_sleep 37
	s_sleep 37
.Llag_LBB0936:
	v_mov_b32_e32 v12, v0
	v_readlane_b32 s1, v245, 2
	s_waitcnt lgkmcnt(0)
	s_barrier
	s_cmpk_gt_i32 s1, 0xaff
	v_readfirstlane_b32 s7, v12
	s_cbranch_scc1 .LBB0_954
	v_lshlrev_b32_e32 v2, 4, v12
	v_add_u32_e32 v3, 0x2000, v2
	v_ashrrev_i32_e32 v4, 31, v3
	v_lshrrev_b32_e32 v4, 22, v4
	v_add_u32_e32 v4, v3, v4
	v_ashrrev_i32_e32 v10, 10, v4
	v_mul_i32_i24_e32 v4, 0x400, v10
	v_sub_u32_e32 v3, v3, v4
	v_lshrrev_b32_e32 v4, 4, v3
	v_bitop3_b32 v3, v4, v3, 32 bitop3:0x6c
	v_ashrrev_i32_e32 v4, 31, v3
	v_lshrrev_b32_e32 v4, 26, v4
	v_add_u32_e32 v4, v3, v4
	v_lshlrev_b32_e32 v5, 3, v10
	v_ashrrev_i32_e32 v11, 6, v4
	v_and_b32_e32 v5, -16, v5
	v_add_u32_e32 v5, v11, v5
	v_and_b32_e32 v6, 3, v11
	s_mov_b32 s0, 0x1fffe0
	v_lshrrev_b32_e32 v7, 2, v5
	v_lshlrev_b32_e32 v8, 1, v5
	v_and_b32_e32 v4, 0xc0, v4
	v_and_or_b32 v6, v5, s0, v6
	v_and_b32_e32 v7, 4, v7
	v_and_b32_e32 v8, 24, v8
	v_sub_u32_e32 v3, v3, v4
	v_mov_b32_e32 v4, 1
	v_or3_b32 v6, v6, v7, v8
	v_lshlrev_b32_e32 v7, 5, v10
	v_ashrrev_i16_sdwa v3, v4, sext(v3) dst_sel:DWORD dst_unused:UNUSED_PAD src0_sel:DWORD src1_sel:BYTE_0
	v_and_b32_e32 v7, 32, v7
	v_bfe_i32 v13, v3, 0, 16
	v_add_lshl_u32 v3, v7, v13, 1
	v_lshl_add_u32 v130, v6, 11, v3
	v_lshl_add_u32 v132, v5, 11, v3
	v_bfe_i32 v3, v12, 27, 1
	v_lshrrev_b32_e32 v3, 22, v3
	v_add_u32_e32 v3, v2, v3
	v_and_b32_e32 v3, 0xfffffc00, v3
	v_sub_u32_e32 v2, v2, v3
	v_lshrrev_b32_e32 v3, 4, v2
	v_ashrrev_i32_e32 v5, 31, v12
	v_bitop3_b32 v2, v3, v2, 32 bitop3:0x6c
	v_lshrrev_b32_e32 v5, 26, v5
	v_ashrrev_i32_e32 v3, 31, v2
	v_add_u32_e32 v5, v12, v5
	v_lshrrev_b32_e32 v3, 26, v3
	v_ashrrev_i32_e32 v15, 6, v5
	v_add_u32_e32 v3, v2, v3
	v_lshlrev_b32_e32 v5, 3, v15
	v_ashrrev_i32_e32 v14, 6, v3
	v_and_b32_e32 v5, -16, v5
	v_add_u32_e32 v5, v14, v5
	v_and_b32_e32 v6, 3, v14
	v_and_or_b32 v6, v5, s0, v6
	s_mul_hi_i32 s0, s1, 0x2e8ba2e9
	s_lshr_b32 s1, s0, 31
	s_ashr_i32 s0, s0, 8
	s_add_i32 s0, s0, s1
	s_mul_hi_i32 s1, s80, 0x2e8ba2e9
	s_lshr_b32 s3, s1, 31
	s_lshr_b32 s1, s1, 5
	s_add_i32 s1, s1, s3
	s_mulk_i32 s1, 0xb0
	s_sub_i32 s1, s80, s1
	s_sext_i32_i16 s3, s1
	s_bfe_u32 s3, s3, 0x3001c
	s_add_i32 s3, s1, s3
	s_sext_i32_i16 s6, s3
	s_and_b32 s3, s3, 0xfff8
	s_sub_i32 s1, s1, s3
	s_lshl_b32 s0, s0, 3
	s_sext_i32_i16 s1, s1
	v_lshrrev_b32_e32 v7, 2, v5
	v_lshlrev_b32_e32 v8, 1, v5
	v_and_b32_e32 v3, 0xc0, v3
	s_lshr_b32 s6, s6, 3
	s_add_i32 s20, s0, s1
	s_ashr_i32 s2, s7, 6
	v_and_b32_e32 v7, 4, v7
	v_and_b32_e32 v8, 24, v8
	v_sub_u32_e32 v2, v2, v3
	s_ashr_i32 s21, s20, 31
	s_bfe_i64 s[10:11], s[6:7], 0x100000
	s_ashr_i32 s8, s7, 8
	s_lshl_b32 s26, s2, 10
	v_or3_b32 v6, v6, v7, v8
	v_lshlrev_b32_e32 v7, 5, v15
	v_ashrrev_i16_sdwa v2, v4, sext(v2) dst_sel:DWORD dst_unused:UNUSED_PAD src0_sel:DWORD src1_sel:BYTE_0
	s_lshl_b64 s[0:1], s[20:21], 19
	s_lshl_b64 s[10:11], s[10:11], 19
	v_readlane_b32 s12, v245, 3
	v_and_b32_e32 v7, 32, v7
	v_bfe_i32 v16, v2, 0, 16
	v_readlane_b32 s13, v245, 4
	s_add_u32 s22, s12, s10
	v_add_lshl_u32 v2, v7, v16, 1
	s_addc_u32 s23, s13, s11
	s_add_i32 s27, s26, 0
	v_lshl_add_u32 v134, v6, 11, v2
	s_add_i32 m0, s27, 0x10000
	v_lshl_add_u32 v136, v5, 11, v2
	global_load_lds_dwordx4 v134, s[22:23]
	s_add_i32 m0, s27, 0x12000
	s_add_u32 s10, s22, 0x40000
	global_load_lds_dwordx4 v130, s[22:23]
	s_addc_u32 s11, s23, 0
	s_add_i32 m0, s27, 0x14000
	v_mov_b32_e32 v135, 0
	global_load_lds_dwordx4 v134, s[10:11]
	s_add_i32 m0, s27, 0x16000
	s_add_u32 s18, s64, s0
	s_addc_u32 s19, s65, s1
	s_add_i32 s28, s27, 0x2000
	global_load_lds_dwordx4 v130, s[10:11]
	s_mov_b32 m0, s27
	s_add_u32 s0, s18, 0x40000
	global_load_lds_dwordx4 v136, s[18:19]
	s_mov_b32 m0, s28
	s_addc_u32 s1, s19, 0
	s_add_i32 s29, s27, 0x4000
	global_load_lds_dwordx4 v132, s[18:19]
	s_mov_b32 m0, s29
	s_add_i32 s30, s27, 0x6000
	global_load_lds_dwordx4 v136, s[0:1]
	s_mov_b32 m0, s30
	v_mov_b32_e32 v131, v135
	global_load_lds_dwordx4 v132, s[0:1]
	v_mov_b32_e32 v137, v135
	v_mov_b32_e32 v133, v135
	s_cmp_eq_u32 s8, 1
	s_mov_b32 s31, 0
	v_lshl_add_u64 v[8:9], s[22:23], 0, v[134:135]
	v_lshl_add_u64 v[6:7], s[22:23], 0, v[130:131]
	v_lshl_add_u64 v[2:3], s[18:19], 0, v[136:137]
	s_cselect_b64 s[0:1], -1, 0
	s_cmp_lg_u32 s8, 1
	v_lshl_add_u64 v[4:5], s[18:19], 0, v[132:133]
	s_cbranch_scc1 .LBB0_939
	s_barrier
